# strategy 4 on the conv phase: static s_setprio 1 for waves 4-7 during the sliding-window conv loop
# baseline (speedup 1.0000x reference)
.LBB0_1005:
	s_cmp_lt_i32 s34, 11
	s_cselect_b64 s[10:11], -1, 0
	s_and_b64 s[6:7], s[10:11], s[6:7]
	s_andn2_b64 vcc, exec, s[6:7]
	s_cbranch_vccnz .LBB0_1012
	v_lshl_or_b32 v1, s2, 9, v0
	s_waitcnt lgkmcnt(0)
	s_mov_b32 s3, 0x160000
	v_cmp_gt_i32_e32 vcc, s3, v1
	s_and_saveexec_b64 s[12:13], vcc
	s_cbranch_execz .LBB0_1011
	s_load_dword s3, s[0:1], 0xd8
	s_add_u32 s14, s70, 0x7900000
	s_addc_u32 s15, s71, 0
	s_add_u32 s16, s14, 0x2c00
	s_addc_u32 s17, s15, 0
	s_add_u32 s18, s70, 0x1600000
	s_addc_u32 s19, s71, 0
	s_mov_b32 s38, 0x2e8ba2e9
	v_mov_b32_e32 v216, 0
	v_mov_b32_e32 v217, 0
	v_mov_b32_e32 v110, v1
	s_waitcnt lgkmcnt(0)
	s_lshl_b32 s3, s3, 9
	s_mov_b32 s39, 0x1d900
	v_cmp_gt_u32_e32 vcc, s39, v110
	s_and_b64 exec, exec, vcc
	s_cbranch_execz .Lcv_done
	v_readfirstlane_b32 s37, v0
	s_nop 1
	s_lshr_b32 s37, s37, 6
	s_cmp_lt_u32 s37, 4
	s_cbranch_scc1 .Lcv_noprio
	s_setprio 1
.Lcv_noprio:
.Lcv_task:
	v_mul_hi_u32 v2, v110, s38
	v_lshrrev_b32_e32 v2, 8, v2
	v_mul_u32_u24_e32 v3, 0x580, v2
	v_sub_u32_e32 v3, v110, v3
	v_lshlrev_b32_e32 v113, 3, v3
	v_mul_u32_u24_e32 v111, 12, v2
	v_add_u32_e32 v112, 12, v111
	v_min_u32_e32 v112, 0x400, v112
	v_lshlrev_b32_e32 v4, 4, v3
	v_add_u32_e32 v5, 0xb000, v4
	global_load_dwordx4 v[72:75], v5, s[54:55]
	global_load_dwordx4 v[76:79], v4, s[54:55]
	v_add_u32_e32 v5, 0x16000, v4
	global_load_dwordx4 v[80:83], v5, s[54:55]
	global_load_dwordx4 v[84:87], v4, s[56:57]
	v_add_u32_e32 v5, 0x10800, v4
	global_load_dwordx4 v[88:91], v5, s[54:55]
	v_add_u32_e32 v5, 0x5800, v4
	global_load_dwordx4 v[92:95], v5, s[54:55]
	v_add_u32_e32 v5, 0x1b800, v4
	global_load_dwordx4 v[96:99], v5, s[54:55]
	v_add_u32_e32 v5, 0x5800, v4
	global_load_dwordx4 v[100:103], v5, s[56:57]
	v_lshlrev_b32_e32 v5, 3, v111
	v_mul_u32_u24_e32 v6, 0x5800, v5
	v_add_u32_e32 v6, v6, v113
	v_mul_u32_u24_e32 v7, 0x2c00, v5
	v_add_u32_e32 v7, v7, v113
	v_and_b32_e32 v5, 0x1ff, v111
	v_cmp_eq_u32_e32 vcc, 0, v5
	s_nop 1
	v_add_u32_e32 v4, 0xffff5000, v6
	v_cndmask_b32_e32 v4, v4, v6, vcc
	global_load_dwordx2 v[52:53], v4, s[14:15]
	global_load_dwordx2 v[68:69], v4, s[16:17]
	v_add_u32_e32 v4, 0xffffa800, v6
	v_cndmask_b32_e32 v4, v4, v6, vcc
	global_load_dwordx2 v[54:55], v4, s[14:15]
	global_load_dwordx2 v[70:71], v4, s[16:17]
	v_lshlrev_b32_e32 v5, 3, v111
	v_mul_u32_u24_e32 v6, 0x5800, v5
	v_add_u32_e32 v6, v6, v113
	v_mul_u32_u24_e32 v7, 0x2c00, v5
	v_add_u32_e32 v7, v7, v113
	v_mov_b32_e32 v117, v7
	global_load_dwordx2 v[8:9], v6, s[14:15]
	global_load_dwordx2 v[24:25], v6, s[16:17]
	v_add_u32_e32 v6, 0x5800, v6
	global_load_dwordx2 v[10:11], v6, s[14:15]
	global_load_dwordx2 v[26:27], v6, s[16:17]
	v_add_u32_e32 v6, 0x5800, v6
	global_load_dwordx2 v[12:13], v6, s[14:15]
	global_load_dwordx2 v[28:29], v6, s[16:17]
	v_add_u32_e32 v6, 0x5800, v6
	global_load_dwordx2 v[14:15], v6, s[14:15]
	global_load_dwordx2 v[30:31], v6, s[16:17]
	v_add_u32_e32 v6, 0x5800, v6
	global_load_dwordx2 v[16:17], v6, s[14:15]
	global_load_dwordx2 v[32:33], v6, s[16:17]
	v_add_u32_e32 v6, 0x5800, v6
	global_load_dwordx2 v[18:19], v6, s[14:15]
	global_load_dwordx2 v[34:35], v6, s[16:17]
	v_add_u32_e32 v6, 0x5800, v6
	global_load_dwordx2 v[20:21], v6, s[14:15]
	global_load_dwordx2 v[36:37], v6, s[16:17]
	v_add_u32_e32 v6, 0x5800, v6
	global_load_dwordx2 v[22:23], v6, s[14:15]
	global_load_dwordx2 v[38:39], v6, s[16:17]
	v_mov_b32_e32 v4, v117
	global_store_dwordx2 v4, v[216:217], s[18:19]
	v_add_u32_e32 v4, 0x2c00, v4
	global_store_dwordx2 v4, v[216:217], s[18:19]
	v_add_u32_e32 v4, 0x2c00, v4
	global_store_dwordx2 v4, v[216:217], s[18:19]
	v_add_u32_e32 v4, 0x2c00, v4
	global_store_dwordx2 v4, v[216:217], s[18:19]
	v_add_u32_e32 v4, 0x2c00, v4
	global_store_dwordx2 v4, v[216:217], s[18:19]
	v_add_u32_e32 v4, 0x2c00, v4
	global_store_dwordx2 v4, v[216:217], s[18:19]
	v_add_u32_e32 v4, 0x2c00, v4
	global_store_dwordx2 v4, v[216:217], s[18:19]
	v_add_u32_e32 v4, 0x2c00, v4
	global_store_dwordx2 v4, v[216:217], s[18:19]
	s_waitcnt vmcnt(24)
	s_mov_b64 s[6:7], exec

.Lcv_done:
	s_setprio 0
	s_nop 0
	s_nop 0
	s_nop 0
	s_nop 0
	s_nop 0
	s_nop 0
	s_nop 0
	s_nop 0
	s_nop 0
